# combo9 = combo6 + adaLN-modulation items dealt from workgroup (bid + G/2) mod G so the third item lands on workgroups with the fewest weight-conversion items
# speedup vs baseline: 1.0022x; 1.0022x over previous
.LBB0_76:
	s_cmpk_gt_i32 s82, 0x23f
	s_cbranch_scc1 .LBB0_83
	v_and_b32_e32 v0, 0xffffffc0, v5
	s_movk_i32 s0, 0x80
	s_mov_b32 s9, 0x12000
	s_add_u32 s4, s6, 0x100000
	v_lshlrev_b32_e32 v2, 5, v4
	v_cmp_gt_i32_e32 vcc, s0, v4
	v_ashrrev_i32_e32 v8, 6, v4
	v_and_b32_e32 v1, 0x1e0, v41
	v_and_b32_e32 v4, 3, v40
	v_mad_i64_i32 v[12:13], s[0:1], v0, s9, 0
	s_addc_u32 s5, s7, 0
	v_add_u32_e32 v1, 0, v1
	v_lshlrev_b32_e32 v3, 4, v8
	v_lshlrev_b32_e32 v4, 2, v4
	s_add_i32 s0, 0, 0x27d20
	v_add3_u32 v18, v1, v3, v4
	v_ashrrev_i32_e32 v1, 31, v0
	v_mov_b32_e32 v20, s0
	s_add_i32 s0, 0, 0x27d08
	v_and_b32_e32 v9, 60, v5
	v_and_b32_e32 v19, 63, v40
	v_lshlrev_b64 v[10:11], 2, v[0:1]
	v_mov_b32_e32 v21, s0
	v_mov_b32_e32 v22, 0x9000000
	s_movk_i32 s14, 0x2000
	s_mov_b64 s[10:11], 0x24000
	v_add_u32_e32 v23, 0, v2
	s_add_i32 s15, 0, 0x27d28
	s_lshr_b32 s100, s68, 1
	s_add_i32 s16, s82, s100
	s_cmp_ge_i32 s16, s68
	s_cselect_b32 s100, s68, 0
	s_sub_i32 s16, s16, s100
	s_branch .LBB0_79
